# u9 + in-proj: half round of tiles by ticket (fast workgroups take the 11th tile) and weight conversion handed out in half-chunks per workgroup by ticket
# baseline (speedup 1.0000x reference)
;     __host__ __device__ bool next(int i, Unit& u) const {
;         const long L = (long)i * G + c; if (L >= nwg) return false;
;         int wgid = (int)L; { const int q = nwg / NXCD, r = nwg % NXCD, xcd = wgid % NXCD, off = wgid / NXCD; wgid = (xcd < r ? xcd * (q + 1) : r * (q + 1) + (xcd - r) * q) + off; }
.LBB0_122:
	s_add_i32 s84, s84, 1
	s_cmp_lt_u32 s84, 10
	s_cbranch_scc1 .Liq_static
	v_readlane_b32 s98, v255, 24
	s_nop 3
	s_add_i32 s98, s98, 1
	s_nop 0
	v_writelane_b32 v255, s98, 24
	s_or_b32 s98, s98, 0x5eed0000
	v_mov_b32_e32 v2, 0x20010
	s_cmp_lg_u32 s3, 0
	s_cbranch_scc1 .Liq_poll
	s_load_dwordx2 s[100:101], s[0:1], 0x88
	s_waitcnt lgkmcnt(0)
	s_add_u32 s100, s100, 0x6703880
	s_addc_u32 s101, s101, 0
	v_mov_b32_e32 v3, 1
	s_mov_b64 s[6:7], exec
	s_mov_b64 exec, 1
	s_nop 1
	global_atomic_add v4, v20, v3, s[100:101] sc0
	s_nop 1
	s_mov_b64 exec, s[6:7]
	s_waitcnt vmcnt(0)
	s_nop 1
	v_readfirstlane_b32 s99, v4
	v_mov_b32_e32 v4, s98
	s_nop 3
	v_mov_b32_e32 v5, s99
	ds_write_b64 v2, v[4:5]
	s_waitcnt lgkmcnt(0)
	s_branch .Liq_have

;     __host__ __device__ bool next(int i, Unit& u) const {
;         const long L = (long)i * G + c; if (L >= nwg) return false;
.Liq_have:
	s_mul_i32 s6, s79, 10
	s_sub_u32 s101, 0xa80, s6
	s_add_u32 s101, s101, s79
	s_lshl_b32 s100, s101, 1
	s_cmp_ge_u32 s99, s100
	s_cbranch_scc0 .Liq_m1
	s_sub_u32 s99, s99, s100

;     __host__ __device__ bool next(int i, Unit& u) const {
;     ...
;         int wgid = (int)L; { const int q = nwg / NXCD, r = nwg % NXCD, xcd = wgid % NXCD, off = wgid / NXCD; wgid = (xcd < r ? xcd * (q + 1) : r * (q + 1) + (xcd - r) * q) + off; }
.Liq_m2:
	s_sub_u32 s100, s101, s79
	s_cmp_eq_u32 s100, 128
	s_cbranch_scc0 .Liq_m3
	s_cmp_lt_u32 s99, 128
	s_cbranch_scc0 .Liq_m3
	s_and_b32 s100, s99, 15
	s_lshl_b32 s100, s100, 3
	s_lshr_b32 s99, s99, 4
	s_add_u32 s99, s99, s100

;     __host__ __device__ bool next(int i, Unit& u) const {
;         const long L = (long)i * G + c; if (L >= nwg) return false;
;         int wgid = (int)L; { const int q = nwg / NXCD, r = nwg % NXCD, xcd = wgid % NXCD, off = wgid / NXCD; wgid = (xcd < r ? xcd * (q + 1) : r * (q + 1) + (xcd - r) * q) + off; }
;         const int nig = wgm * nN, gid = wgid / nig, fm = gid * wgm, gsz = (nM - fm) < wgm ? (nM - fm) : wgm;
;         u.pm = fm + ((wgid % nig) % gsz); u.pn = (wgid % nig) / gsz; if (rev) u.pm = nM - 1 - u.pm; return true;
.Liq_static:
	s_mul_i32 s4, s84, s82
	s_mul_hi_u32 s5, s84, s79
	s_add_i32 s5, s5, s4
	s_mul_i32 s4, s84, s79
	s_add_u32 s6, s4, s80
	s_addc_u32 s7, s5, s83
.Liq_join:
	v_mov_b64_e32 v[0:1], 0xa80
	v_cmp_lt_i64_e64 s[4:5], s[6:7], v[0:1]
	v_mov_b64_e32 v[0:1], 0xa7f
	v_cmp_gt_i64_e32 vcc, s[6:7], v[0:1]
	s_cbranch_vccnz .LBB0_124
	s_ashr_i32 s7, s6, 31
	s_lshr_b32 s7, s7, 29
	s_add_i32 s7, s6, s7
	s_ashr_i32 s24, s7, 3
	s_and_b32 s7, s7, -8
	s_sub_i32 s6, s6, s7
	s_cmp_lt_i32 s6, 0
	s_cselect_b32 s7, s30, 0x150
	s_mul_i32 s6, s6, s7
	s_add_i32 s6, s6, s24
	s_mul_hi_i32 s7, s6, 0x30c30c31
	s_lshr_b32 s24, s7, 31
	s_ashr_i32 s7, s7, 4
	s_add_i32 s7, s7, s24
	s_lshl_b32 s24, s7, 2
	s_sub_i32 s25, 0x80, s24
	s_min_i32 s25, s25, 4
	s_abs_i32 s60, s25
	v_cvt_f32_u32_e32 v0, s60
	s_sub_i32 s62, 0, s60
	s_mulk_i32 s7, 0x54
	s_sub_i32 s6, s6, s7
	v_rcp_iflag_f32_e32 v0, v0
	s_abs_i32 s7, s6
	s_xor_b32 s61, s6, s25
	s_ashr_i32 s61, s61, 31
	v_mul_f32_e32 v0, 0x4f7ffffe, v0
	v_cvt_u32_f32_e32 v0, v0
	s_nop 0
	v_readfirstlane_b32 s63, v0
	s_mul_i32 s62, s62, s63
	s_mul_hi_u32 s62, s63, s62
	s_add_i32 s63, s63, s62
	s_mul_hi_u32 s62, s7, s63
	s_mul_i32 s63, s62, s60
	s_sub_i32 s7, s7, s63
	s_add_i32 s64, s62, 1
	s_sub_i32 s63, s7, s60
	s_cmp_ge_u32 s7, s60
	s_cselect_b32 s62, s64, s62
	s_cselect_b32 s7, s63, s7
	s_add_i32 s63, s62, 1
	s_cmp_ge_u32 s7, s60
	s_cselect_b32 s7, s63, s62
	s_xor_b32 s7, s7, s61
	s_sub_i32 s60, s7, s61
	s_mul_i32 s7, s60, s25
	s_sub_i32 s6, s6, s7
	s_add_i32 s62, s24, s6

; #define LAS __attribute__((address_space(3)))
; __global__ void __launch_bounds__(NWAVES * 64, 2) fwd_mega(Args args_unused) {
;     ...
;             { constexpr int NT_IN = (MTOK / 256) * (PW / 256); const int nfull = NT_IN % G;
;               if (nfull > 0 && bx >= nfull) {
;                   LAS float* scr = (LAS float*)(lds + wave * 16384);
;                   const float* w_out = ap->in[10] + (size_t)l * DM * DM; const float* w_down = ap->in[15] + (size_t)l * DFF * DM; const float* w_up = ap->in[12] + (size_t)l * DM * UW;
;                   bf16* Wt_out = (bf16*)(ws + WS_WOUT); bf16* Wt_down = (bf16*)(ws + WS_WDOWN); bf16* Wt_up = (bf16*)(ws + WS_WUP);
;                   constexpr int I_OUT = (DM / 64) * (DM / 32), I_DOWN = (DFF / 64) * (DM / 32), I_UP = (DM / 64) * (UW / 32);
;                   const int nw = (G - nfull) * NWAVES;
;                   for (int it = (bx - nfull) * NWAVES + wave; it < I_OUT + I_DOWN + I_UP; it += nw) {
;                       if (it < I_OUT) transpose_item(w_out, DM, DM, Wt_out, scr, it, lane); else if (it < I_OUT + I_DOWN) transpose_item(w_down, DFF, DM, Wt_down, scr, it - I_OUT, lane);
;                       else transpose_item(w_up, DM, UW, Wt_up, scr, it - I_OUT - I_DOWN, lane, true, ap->in[11] + (size_t)l * DM); }
;               } else if (nfull == 0) {
;                   LAS float* scr = (LAS float*)(lds + wave * 16384);
;                   const float* w_out = ap->in[10] + (size_t)l * DM * DM; const float* w_down = ap->in[15] + (size_t)l * DFF * DM; const float* w_up = ap->in[12] + (size_t)l * DM * UW;
;                   bf16* Wt_out = (bf16*)(ws + WS_WOUT); bf16* Wt_down = (bf16*)(ws + WS_WDOWN); bf16* Wt_up = (bf16*)(ws + WS_WUP);
;                   constexpr int I_OUT = (DM / 64) * (DM / 32), I_DOWN = (DFF / 64) * (DM / 32), I_UP = (DM / 64) * (UW / 32);
;                   for (int it = gw; it < I_OUT + I_DOWN + I_UP; it += NGW) {
;                       if (it < I_OUT) transpose_item(w_out, DM, DM, Wt_out, scr, it, lane); else if (it < I_OUT + I_DOWN) transpose_item(w_down, DFF, DM, Wt_down, scr, it - I_OUT, lane);
;                       else transpose_item(w_up, DM, UW, Wt_up, scr, it - I_OUT - I_DOWN, lane, true, ap->in[11] + (size_t)l * DM); }
;               } }
.LBB0_159:
	s_abs_i32 s4, s79
	v_cvt_f32_u32_e32 v0, s4
	s_sub_i32 s5, 0, s4
	v_rcp_iflag_f32_e32 v0, v0
	s_nop 0
	v_mul_f32_e32 v0, 0x4f7ffffe, v0
	v_cvt_u32_f32_e32 v0, v0
	s_nop 0
	v_readfirstlane_b32 s6, v0
	s_mul_i32 s5, s5, s6
	s_mul_hi_u32 s5, s6, s5
	s_add_i32 s6, s6, s5
	s_mul_hi_u32 s5, s6, 0xa80
	s_mul_i32 s5, s5, s4
	s_sub_i32 s5, 0xa80, s5
	s_sub_i32 s6, s5, s4
	s_cmp_ge_u32 s5, s4
	s_cselect_b32 s5, s6, s5
	s_sub_i32 s6, s5, s4
	s_cmp_ge_u32 s5, s4
	s_cselect_b32 s8, s6, s5
	s_cmp_eq_u32 s8, 0
	s_cselect_b64 s[4:5], -1, 0
	s_cmp_lt_i32 s80, s8
	s_mov_b64 s[6:7], 0
	s_or_b64 s[10:11], s[4:5], s[6:7]
	s_mov_b64 s[6:7], -1
	s_and_b64 vcc, exec, s[10:11]
	s_cbranch_vccnz .LBB0_176
	s_mov_b32 s99, 0
	s_branch .Lcw_get
.Lcw_init_cont:
	s_cmpk_gt_i32 s10, 0x49ff
	s_cbranch_scc1 .LBB0_175
	s_sub_i32 s16, s79, s8
	s_lshl_b32 s11, s16, 3
	s_add_u32 s6, s0, s76
	s_addc_u32 s7, s1, s77
	s_load_dwordx2 s[8:9], s[6:7], 0x60
	s_load_dwordx2 s[14:15], s[6:7], 0x78
	s_nop 0
	s_load_dwordx2 s[6:7], s[6:7], 0x50
	s_mul_i32 s18, s44, 0x5800000
	s_mul_hi_u32 s12, s44, 0x5800000
	v_lshlrev_b32_e32 v0, 2, v21
	s_waitcnt lgkmcnt(0)
	s_add_u32 s8, s8, s18
	s_addc_u32 s9, s9, s12
	s_mul_i32 s18, s44, 0x2c00000
	s_mul_hi_u32 s12, s44, 0x2c00000
	s_add_u32 s14, s14, s18
	s_addc_u32 s15, s15, s12
	s_lshl_b64 s[26:27], s[44:45], 24
	s_add_u32 s6, s6, s26
	s_addc_u32 s7, s7, s27
	s_lshl_b32 s12, s78, 14
	v_and_b32_e32 v3, 7, v21
	s_waitcnt vmcnt(6)
	v_ashrrev_i32_e32 v24, 3, v21
	s_add_i32 s12, s12, 0
	v_and_b32_e32 v0, 0x7c, v0
	v_mov_b32_e32 v1, v20
	v_mul_u32_u24_e32 v4, 0x420, v3
	v_lshlrev_b32_e32 v5, 2, v24
	v_ashrrev_i32_e32 v22, 5, v21
	v_lshl_add_u64 v[8:9], s[8:9], 0, v[0:1]
	s_movk_i32 s8, 0x84
	v_add3_u32 v25, s12, v4, v5
	v_lshlrev_b32_e32 v4, 4, v3
	v_mov_b32_e32 v5, v20
	v_mul_lo_u32 v2, v22, s8
	v_lshl_add_u64 v[4:5], s[50:51], 0, v[4:5]
	v_lshl_add_u64 v[14:15], s[6:7], 0, v[0:1]
	s_mov_b64 s[6:7], 0x1500000
	v_add3_u32 v23, s12, v0, v2
	v_lshlrev_b32_e32 v2, 3, v3
	s_mov_b64 s[8:9], 0x4900000
	v_lshl_add_u64 v[16:17], v[4:5], 0, s[6:7]
	s_mov_b64 s[6:7], 0x1d00000
	s_waitcnt vmcnt(5)
	v_add_u32_e32 v26, 8, v24
	v_add_u32_e32 v27, 16, v24
	v_add_u32_e32 v28, 24, v24
	v_lshl_add_u64 v[10:11], s[14:15], 0, v[0:1]
	v_lshl_add_u64 v[12:13], v[4:5], 0, s[8:9]
	v_lshl_add_u64 v[18:19], v[4:5], 0, s[6:7]
	s_lshl_b32 s12, s10, 5
	s_lshl_b32 s14, s16, 8
	v_lshlrev_b32_e32 v29, 2, v2
	s_movk_i32 s11, 0x400
	s_mov_b32 s14, 0x8000
	s_or_b32 s99, s99, 2
	s_branch .LBB0_163
.Lcw_get:
	s_barrier
	v_readlane_b32 s100, v255, 24
	s_nop 3
	s_add_i32 s100, s100, 1
	s_nop 0
	v_writelane_b32 v255, s100, 24
	s_or_b32 s100, s100, 0x5eed0000
	s_mov_b64 s[6:7], exec
	s_mov_b64 exec, -1
	s_nop 1
	v_mov_b32_e32 v240, 0x20010
	s_cmp_lg_u32 s78, 0
	s_cbranch_scc1 .Lcw_poll
	s_load_dwordx2 s[10:11], s[0:1], 0x88
	s_waitcnt lgkmcnt(0)
	s_add_u32 s10, s10, 0x67038c0
	s_addc_u32 s11, s11, 0
	v_mov_b32_e32 v241, 1
	s_mov_b64 exec, 1
	s_nop 1
	global_atomic_add v242, v20, v241, s[10:11] sc0
	s_nop 1
	s_mov_b64 exec, -1
	s_waitcnt vmcnt(0)
	s_nop 1
	v_readlane_b32 s101, v242, 0
	v_mov_b32_e32 v242, s100
	s_nop 3
	v_mov_b32_e32 v243, s101
	ds_write_b64 v240, v[242:243]
	s_waitcnt lgkmcnt(0)
	s_branch .Lcw_have
.Lcw_poll:
	s_mov_b32 s10, 0x100000
.Lcw_spin:
	ds_read_b64 v[242:243], v240
	s_waitcnt lgkmcnt(0)
	v_readlane_b32 s11, v242, 0
	v_readlane_b32 s101, v243, 0
	s_nop 3
	s_cmp_eq_u32 s11, s100
	s_cbranch_scc1 .Lcw_have
	s_sleep 1
	s_sub_u32 s10, s10, 1
	s_cmp_lg_u32 s10, 0
	s_cbranch_scc1 .Lcw_spin
	s_mov_b32 s101, 0x1ff
.Lcw_have:
	s_mov_b64 exec, s[6:7]
	s_movk_i32 s11, 0x400
	s_and_b32 s101, s101, 0x1ff
	s_cmp_lt_u32 s101, 0x100
	s_cbranch_scc0 .LBB0_175
	s_lshr_b32 s10, s101, 1
	s_lshl_b32 s10, s10, 3
	s_add_i32 s10, s10, s78
	s_and_b32 s101, s101, 1
	s_mul_i32 s101, s101, 0x2800
	s_add_u32 s10, s10, s101
	s_add_u32 s98, s10, 0x2800
	s_lshl_b32 s12, s10, 5
	s_bitcmp1_b32 s99, 1
	s_cbranch_scc1 .LBB0_163
	s_branch .Lcw_init_cont
.LBB0_162:
	s_add_i32 s10, s10, s11
	s_add_i32 s12, s12, s14
	s_cmpk_gt_i32 s10, 0x49ff
	s_cbranch_scc1 .Lcw_get
	s_cmp_lt_u32 s10, s98
	s_cbranch_scc0 .Lcw_get
